# P1 and P7 row-norm reductions: ds_bpermute butterfly replaced by DPP adds plus one permlane16 swap (bit-identical sums)
# baseline (speedup 1.0000x reference)
; __device__ __forceinline__ void modnorm_row(const float* xr, const float* pre_g, const float* modrow, bf16_t* hrow, int l32) {
;     f32x4 v[8]; float s = 0.f;
; #pragma unroll
;     for (int j = 0; j < 4; ++j) { v[2 * j] = *(const f32x4*)(xr + 8 * l32 + 256 * j); v[2 * j + 1] = *(const f32x4*)(xr + 8 * l32 + 256 * j + 4); }
; #pragma unroll
;     for (int j = 0; j < 8; ++j) s += v[j][0] * v[j][0] + v[j][1] * v[j][1] + v[j][2] * v[j][2] + v[j][3] * v[j][3];
; #pragma unroll
;     for (int o = 1; o < 32; o <<= 1) s += __shfl_xor(s, o);
;     const float rs = __builtin_amdgcn_rsqf(s * (1.f / D) + EPS);
; #pragma unroll
;     for (int j = 0; j < 4; ++j) { float o[8];
; #pragma unroll
;         for (int q = 0; q < 2; ++q) { const int c = 8 * l32 + 256 * j + 4 * q;
;             const f32x4 g = *(const f32x4*)(pre_g + c), sh = *(const f32x4*)(modrow + c), sc = *(const f32x4*)(modrow + D + c);
; #pragma unroll
;             for (int e = 0; e < 4; ++e) o[4 * q + e] = v[2 * j + q][e] * rs * g[e] * (1.f + sc[e]) + sh[e]; }
.LBB0_164:
	s_or_b64 exec, exec, s[14:15]
	v_lshl_add_u64 v[40:41], v[0:1], 0, v[24:25]
	global_load_dwordx4 v[50:53], v[40:41], off
	global_load_dwordx4 v[54:57], v[40:41], off offset:16
	global_load_dwordx4 v[20:23], v[40:41], off offset:1024
	global_load_dwordx4 v[16:19], v[40:41], off offset:1040
	global_load_dwordx4 v[12:15], v[40:41], off offset:2048
	global_load_dwordx4 v[8:11], v[40:41], off offset:2064
	global_load_dwordx4 v[4:7], v[40:41], off offset:3072
	global_load_dwordx4 v[0:3], v[40:41], off offset:3088
	v_lshl_add_u64 v[36:37], v[36:37], 2, s[24:25]
	v_lshl_add_u64 v[40:41], v[36:37], 0, s[12:13]
	v_lshl_add_u64 v[74:75], v[40:41], 0, v[24:25]
	global_load_dwordx4 v[58:61], v[74:75], off offset:16
	global_load_dwordx4 v[62:65], v[74:75], off
	global_load_dwordx4 v[66:69], v[28:29], off offset:16
	global_load_dwordx4 v[70:73], v[28:29], off
	v_lshl_add_u64 v[36:37], v[36:37], 0, v[24:25]
	global_load_dwordx4 v[74:77], v[36:37], off offset:16
	global_load_dwordx4 v[78:81], v[36:37], off
	s_add_i32 s17, s17, s16
	s_cmp_lt_i32 s17, 0x12000
	s_waitcnt vmcnt(13)
	v_mul_f32_e32 v39, v51, v51
	s_waitcnt vmcnt(12)
	v_mul_f32_e32 v49, v55, v55
	s_waitcnt vmcnt(11)
	v_mul_f32_e32 v98, v21, v21
	v_fmac_f32_e32 v39, v50, v50
	v_fmac_f32_e32 v49, v54, v54
	s_waitcnt vmcnt(10)
	v_mul_f32_e32 v99, v17, v17
	s_waitcnt vmcnt(9)
	v_mov_b32_e32 v84, v13
	s_waitcnt vmcnt(8)
	v_mov_b32_e32 v85, v9
	v_fmac_f32_e32 v98, v20, v20
	v_fmac_f32_e32 v39, v52, v52
	v_fmac_f32_e32 v49, v56, v56
	v_mov_b32_e32 v82, v12
	v_mov_b32_e32 v83, v8
	v_fmac_f32_e32 v99, v16, v16
	v_pk_mul_f32 v[84:85], v[84:85], v[84:85]
	v_fmac_f32_e32 v98, v22, v22
	v_fmac_f32_e32 v39, v53, v53
	v_fmac_f32_e32 v49, v57, v57
	v_mov_b32_e32 v86, v14
	v_mov_b32_e32 v87, v10
	s_waitcnt vmcnt(7)
	v_mov_b32_e32 v92, v5
	s_waitcnt vmcnt(6)
	v_mov_b32_e32 v93, v1
	v_fmac_f32_e32 v99, v18, v18
	v_pk_fma_f32 v[82:83], v[82:83], v[82:83], v[84:85]
	v_fmac_f32_e32 v98, v23, v23
	v_add_f32_e32 v39, v39, v49
	v_mov_b32_e32 v88, v15
	v_mov_b32_e32 v89, v11
	v_mov_b32_e32 v90, v4
	v_mov_b32_e32 v91, v0
	v_pk_mul_f32 v[92:93], v[92:93], v[92:93]
	v_fmac_f32_e32 v99, v19, v19
	v_pk_fma_f32 v[82:83], v[86:87], v[86:87], v[82:83]
	v_add_f32_e32 v39, v39, v98
	v_mov_b32_e32 v94, v6
	v_mov_b32_e32 v95, v2
	v_pk_fma_f32 v[84:85], v[90:91], v[90:91], v[92:93]
	v_pk_fma_f32 v[82:83], v[88:89], v[88:89], v[82:83]
	v_add_f32_e32 v39, v39, v99
	v_mov_b32_e32 v96, v7
	v_mov_b32_e32 v97, v3
	v_pk_fma_f32 v[84:85], v[94:95], v[94:95], v[84:85]
	v_add_f32_e32 v39, v39, v82
	v_pk_fma_f32 v[84:85], v[96:97], v[96:97], v[84:85]
	v_add_f32_e32 v39, v39, v83
	v_add_f32_e32 v39, v39, v84
	v_add_f32_e32 v39, v39, v85
	s_waitcnt vmcnt(4)
	v_pk_add_f32 v[62:63], v[62:63], 1.0 op_sel_hi:[1,0]
	v_pk_add_f32 v[64:65], v[64:65], 1.0 op_sel_hi:[1,0]
	v_pk_add_f32 v[58:59], v[58:59], 1.0 op_sel_hi:[1,0]
	v_pk_add_f32 v[60:61], v[60:61], 1.0 op_sel_hi:[1,0]
	s_waitcnt lgkmcnt(0)
	s_nop 1
	v_add_f32_dpp v39, v39, v39 quad_perm:[1,0,3,2] row_mask:0xf bank_mask:0xf
	s_waitcnt lgkmcnt(0)
	s_nop 1
	v_add_f32_dpp v39, v39, v39 quad_perm:[2,3,0,1] row_mask:0xf bank_mask:0xf
	s_waitcnt lgkmcnt(0)
	s_nop 1
	v_add_f32_dpp v49, v39, v39 row_half_mirror row_mask:0xf bank_mask:0xf
	v_ashrrev_i32_e32 v39, 31, v38
	v_lshlrev_b64 v[38:39], 11, v[38:39]
	v_lshl_add_u64 v[38:39], v[26:27], 0, v[38:39]
	s_waitcnt lgkmcnt(0)
	s_nop 1
	v_add_f32_dpp v49, v49, v49 row_mirror row_mask:0xf bank_mask:0xf
	v_lshl_add_u64 v[82:83], v[40:41], 0, v[30:31]
	s_waitcnt lgkmcnt(0)
	v_mov_b32_e32 v84, v49
	s_nop 1
	v_permlane16_swap_b32_e32 v84, v49
	v_add_f32_e32 v49, v49, v84
	v_fmamk_f32 v49, v49, 0x3a800000, v48
	v_rsq_f32_e32 v84, v49
	s_nop 0
	v_pk_mul_f32 v[50:51], v[50:51], v[84:85] op_sel_hi:[1,0]
	v_pk_mul_f32 v[52:53], v[52:53], v[84:85] op_sel_hi:[1,0]
	v_pk_mul_f32 v[54:55], v[54:55], v[84:85] op_sel_hi:[1,0]
	v_pk_mul_f32 v[56:57], v[56:57], v[84:85] op_sel_hi:[1,0]
	s_waitcnt vmcnt(2)
	v_pk_mul_f32 v[50:51], v[70:71], v[50:51]
	v_pk_mul_f32 v[52:53], v[72:73], v[52:53]
	v_pk_mul_f32 v[54:55], v[66:67], v[54:55]
	v_pk_mul_f32 v[56:57], v[68:69], v[56:57]
	s_waitcnt vmcnt(0)
; __device__ __forceinline__ unsigned cvtpk(float lo, float hi) { f32x2 v = {lo, hi}; bf16x2_t b = __builtin_convertvector(v, bf16x2_t); return __builtin_bit_cast(unsigned, b); }
; __device__ __forceinline__ void modnorm_row(const float* xr, const float* pre_g, const float* modrow, bf16_t* hrow, int l32) {
;     ...
; #pragma unroll
;     for (int j = 0; j < 4; ++j) { float o[8];
; #pragma unroll
;         for (int q = 0; q < 2; ++q) { const int c = 8 * l32 + 256 * j + 4 * q;
;             const f32x4 g = *(const f32x4*)(pre_g + c), sh = *(const f32x4*)(modrow + c), sc = *(const f32x4*)(modrow + D + c);
; #pragma unroll
;             for (int e = 0; e < 4; ++e) o[4 * q + e] = v[2 * j + q][e] * rs * g[e] * (1.f + sc[e]) + sh[e]; }
;         u32x4 pk; pk.x = cvtpk(o[0], o[1]); pk.y = cvtpk(o[2], o[3]); pk.z = cvtpk(o[4], o[5]); pk.w = cvtpk(o[6], o[7]);
;         *(u32x4*)(hrow + 8 * l32 + 256 * j) = pk; }
	v_pk_fma_f32 v[50:51], v[62:63], v[50:51], v[78:79]
	v_pk_fma_f32 v[52:53], v[64:65], v[52:53], v[80:81]
	v_pk_fma_f32 v[54:55], v[58:59], v[54:55], v[74:75]
	v_pk_fma_f32 v[56:57], v[60:61], v[56:57], v[76:77]
	v_cvt_pk_bf16_f32 v50, v50, v51
	v_cvt_pk_bf16_f32 v51, v52, v53
	v_cvt_pk_bf16_f32 v52, v54, v55
	v_cvt_pk_bf16_f32 v53, v56, v57
	global_store_dwordx4 v[38:39], v[50:53], off
	global_load_dwordx4 v[50:53], v[28:29], off offset:1024
	s_nop 0
	global_load_dwordx4 v[54:57], v[82:83], off
	global_load_dwordx4 v[58:61], v[28:29], off offset:1040
	global_load_dwordx4 v[62:65], v[82:83], off offset:16
	global_load_dwordx4 v[66:69], v[36:37], off offset:1024
	global_load_dwordx4 v[70:73], v[36:37], off offset:1040
	v_pk_mul_f32 v[20:21], v[20:21], v[84:85] op_sel_hi:[1,0]
	v_pk_mul_f32 v[22:23], v[22:23], v[84:85] op_sel_hi:[1,0]
	v_pk_mul_f32 v[16:17], v[16:17], v[84:85] op_sel_hi:[1,0]
	v_pk_mul_f32 v[18:19], v[18:19], v[84:85] op_sel_hi:[1,0]
	v_lshl_add_u64 v[74:75], v[40:41], 0, v[32:33]
	v_pk_mul_f32 v[12:13], v[12:13], v[84:85] op_sel_hi:[1,0]
	v_pk_mul_f32 v[14:15], v[14:15], v[84:85] op_sel_hi:[1,0]
	v_pk_mul_f32 v[8:9], v[8:9], v[84:85] op_sel_hi:[1,0]
	v_pk_mul_f32 v[10:11], v[10:11], v[84:85] op_sel_hi:[1,0]
	v_lshl_add_u64 v[40:41], v[40:41], 0, v[34:35]
	v_pk_mul_f32 v[4:5], v[4:5], v[84:85] op_sel_hi:[1,0]
	v_pk_mul_f32 v[6:7], v[6:7], v[84:85] op_sel_hi:[1,0]
	v_pk_mul_f32 v[0:1], v[0:1], v[84:85] op_sel_hi:[1,0]
	v_pk_mul_f32 v[2:3], v[2:3], v[84:85] op_sel_hi:[1,0]
	s_waitcnt vmcnt(5)
	v_pk_mul_f32 v[20:21], v[50:51], v[20:21]
	s_waitcnt vmcnt(4)
	v_pk_add_f32 v[50:51], v[54:55], 1.0 op_sel_hi:[1,0]
	v_pk_mul_f32 v[22:23], v[52:53], v[22:23]
	v_pk_add_f32 v[52:53], v[56:57], 1.0 op_sel_hi:[1,0]
	s_waitcnt vmcnt(3)
	v_pk_mul_f32 v[16:17], v[16:17], v[58:59]
	s_waitcnt vmcnt(2)
	v_pk_add_f32 v[54:55], v[62:63], 1.0 op_sel_hi:[1,0]
	v_pk_mul_f32 v[18:19], v[18:19], v[60:61]
	v_pk_add_f32 v[56:57], v[64:65], 1.0 op_sel_hi:[1,0]
	s_waitcnt vmcnt(1)
	v_pk_fma_f32 v[20:21], v[20:21], v[50:51], v[66:67]
	v_pk_fma_f32 v[22:23], v[22:23], v[52:53], v[68:69]
	s_waitcnt vmcnt(0)
	v_pk_fma_f32 v[50:51], v[16:17], v[54:55], v[70:71]
	v_pk_fma_f32 v[52:53], v[18:19], v[56:57], v[72:73]
	v_cvt_pk_bf16_f32 v16, v20, v21
	v_cvt_pk_bf16_f32 v17, v22, v23
	v_cvt_pk_bf16_f32 v18, v50, v51
	v_cvt_pk_bf16_f32 v19, v52, v53
	global_store_dwordx4 v[38:39], v[16:19], off offset:512
	global_load_dwordx4 v[16:19], v[28:29], off offset:2048
	s_nop 0
	global_load_dwordx4 v[20:23], v[74:75], off
	global_load_dwordx4 v[50:53], v[28:29], off offset:2064
	global_load_dwordx4 v[54:57], v[74:75], off offset:16
	global_load_dwordx4 v[58:61], v[36:37], off offset:2048
	global_load_dwordx4 v[62:65], v[36:37], off offset:2064
	s_waitcnt vmcnt(5)
	v_pk_mul_f32 v[12:13], v[12:13], v[16:17]
	s_waitcnt vmcnt(4)
	v_pk_add_f32 v[16:17], v[20:21], 1.0 op_sel_hi:[1,0]
	v_pk_mul_f32 v[14:15], v[14:15], v[18:19]
	v_pk_add_f32 v[18:19], v[22:23], 1.0 op_sel_hi:[1,0]
	s_waitcnt vmcnt(3)
	v_pk_mul_f32 v[8:9], v[8:9], v[50:51]
	s_waitcnt vmcnt(2)
	v_pk_add_f32 v[20:21], v[54:55], 1.0 op_sel_hi:[1,0]
	v_pk_mul_f32 v[10:11], v[10:11], v[52:53]
	v_pk_add_f32 v[22:23], v[56:57], 1.0 op_sel_hi:[1,0]
	s_waitcnt vmcnt(1)
	v_pk_fma_f32 v[12:13], v[12:13], v[16:17], v[58:59]
	v_pk_fma_f32 v[14:15], v[14:15], v[18:19], v[60:61]
	s_waitcnt vmcnt(0)
	v_pk_fma_f32 v[16:17], v[8:9], v[20:21], v[62:63]
	v_pk_fma_f32 v[18:19], v[10:11], v[22:23], v[64:65]
	v_cvt_pk_bf16_f32 v8, v12, v13
	v_cvt_pk_bf16_f32 v9, v14, v15
	v_cvt_pk_bf16_f32 v10, v16, v17
	v_cvt_pk_bf16_f32 v11, v18, v19
	global_store_dwordx4 v[38:39], v[8:11], off offset:1024
	global_load_dwordx4 v[8:11], v[28:29], off offset:3072
	s_nop 0
	global_load_dwordx4 v[12:15], v[40:41], off
	global_load_dwordx4 v[16:19], v[28:29], off offset:3088
	global_load_dwordx4 v[20:23], v[40:41], off offset:16
	global_load_dwordx4 v[50:53], v[36:37], off offset:3072
	global_load_dwordx4 v[54:57], v[36:37], off offset:3088
	s_waitcnt vmcnt(5)
	v_pk_mul_f32 v[4:5], v[4:5], v[8:9]
	s_waitcnt vmcnt(4)
	v_pk_add_f32 v[8:9], v[12:13], 1.0 op_sel_hi:[1,0]
	v_pk_mul_f32 v[6:7], v[6:7], v[10:11]
	v_pk_add_f32 v[10:11], v[14:15], 1.0 op_sel_hi:[1,0]
	s_waitcnt vmcnt(3)
	v_pk_mul_f32 v[0:1], v[0:1], v[16:17]
	s_waitcnt vmcnt(2)
	v_pk_add_f32 v[12:13], v[20:21], 1.0 op_sel_hi:[1,0]
	v_pk_mul_f32 v[2:3], v[2:3], v[18:19]
	v_pk_add_f32 v[14:15], v[22:23], 1.0 op_sel_hi:[1,0]
	s_waitcnt vmcnt(1)
	v_pk_fma_f32 v[4:5], v[4:5], v[8:9], v[50:51]
	v_pk_fma_f32 v[6:7], v[6:7], v[10:11], v[52:53]
	s_waitcnt vmcnt(0)
	v_pk_fma_f32 v[8:9], v[0:1], v[12:13], v[54:55]
	v_pk_fma_f32 v[10:11], v[2:3], v[14:15], v[56:57]
	v_cvt_pk_bf16_f32 v0, v4, v5
	v_cvt_pk_bf16_f32 v1, v6, v7
	v_cvt_pk_bf16_f32 v2, v8, v9
	v_cvt_pk_bf16_f32 v3, v10, v11
	global_store_dwordx4 v[38:39], v[0:3], off offset:1536
	s_cbranch_scc0 .LBB0_169

; __device__ __forceinline__ float bflo(unsigned u) { return __uint_as_float(u << 16); }
; __device__ __forceinline__ float bfhi(unsigned u) { return __uint_as_float(u & 0xffff0000u); }
; __global__ void __launch_bounds__(512, 2) fwd_kernel(Params p) {
;     ...
;             const int l32 = lane & 31; const int r = r0 + (lane >> 5);
;             const int b = r / TOK, tok = r % TOK; const bool isctx = tok < CTXL;
;             if (l == 1 && (r0 % TOK) < CTXL) continue;
;             const bf16_t* orow = Z + (size_t)r * ZP + 1024;
;             const float* xr = (l == 0) ? (isctx ? p.ctx + ((size_t)b * CTXL + tok) * D : p.x + ((size_t)b * SEQ + tok - CTXL) * D) : p.out + ((size_t)b * SEQ + tok - CTXL) * D;
;             const float* mrow = modb + ((size_t)l * 33 + (isctx ? 32 : b)) * 3072;
;             u32x4 t4[4]; f32x4 xv[8];
; #pragma unroll
;             for (int j = 0; j < 4; ++j) { t4[j] = *(const u32x4*)(orow + 8 * l32 + 256 * j); xv[2 * j] = *(const f32x4*)(xr + 8 * l32 + 256 * j); xv[2 * j + 1] = *(const f32x4*)(xr + 8 * l32 + 256 * j + 4); }
;             float ov[32]; float s = 0.f;
; #pragma unroll
;             for (int j = 0; j < 4; ++j) {
;                 ov[8 * j + 0] = bflo(t4[j].x); ov[8 * j + 1] = bfhi(t4[j].x); ov[8 * j + 2] = bflo(t4[j].y); ov[8 * j + 3] = bfhi(t4[j].y); ov[8 * j + 4] = bflo(t4[j].z); ov[8 * j + 5] = bfhi(t4[j].z); ov[8 * j + 6] = bflo(t4[j].w); ov[8 * j + 7] = bfhi(t4[j].w); }
; #pragma unroll
;             for (int j = 0; j < 32; ++j) s += ov[j] * ov[j];
; #pragma unroll
;             for (int o = 1; o < 32; o <<= 1) s += __shfl_xor(s, o);
;             const float rs = __builtin_amdgcn_rsqf(s * (1.f / D) + EPS);
;             float s2 = 0.f;
; #pragma unroll
;             for (int j = 0; j < 4; ++j)
; #pragma unroll
;                 for (int q = 0; q < 2; ++q) { const int c = 8 * l32 + 256 * j + 4 * q;
;                     const f32x4 pg = *(const f32x4*)(p.post_norm + l * D + c), gt = *(const f32x4*)(mrow + 2 * D + c);
; #pragma unroll
;                     for (int e = 0; e < 4; ++e) { const float v = xv[2 * j + q][e] + gt[e] * ov[8 * j + 4 * q + e] * rs * pg[e]; ov[8 * j + 4 * q + e] = v; s2 += v * v; } }
.LBB0_1281:
	v_and_b32_e32 v36, 64, v203
	v_add_u32_e32 v36, 64, v36
	v_xor_b32_e32 v37, 1, v203
	v_cmp_lt_i32_e32 vcc, v37, v36
	v_cndmask_b32_e64 v100, v2, 32, s[40:41]
	v_ashrrev_i32_e32 v101, 31, v100
	v_cndmask_b32_e32 v37, v203, v37, vcc
	v_lshlrev_b32_e32 v77, 2, v37
	v_xor_b32_e32 v37, 2, v203
	v_cmp_lt_i32_e32 vcc, v37, v36
	v_lshl_add_u64 v[34:35], s[8:9], 0, v[100:101]
	s_movk_i32 s17, 0x3000
	v_cndmask_b32_e32 v37, v203, v37, vcc
	v_lshlrev_b32_e32 v79, 2, v37
	v_xor_b32_e32 v37, 4, v203
	v_cmp_lt_i32_e32 vcc, v37, v36
	v_lshlrev_b32_e32 v0, 2, v70
	v_mad_i64_i32 v[2:3], s[2:3], v92, s13, v[90:91]
	v_cndmask_b32_e32 v37, v203, v37, vcc
	v_lshlrev_b32_e32 v81, 2, v37
	v_xor_b32_e32 v37, 8, v203
	v_cmp_lt_i32_e32 vcc, v37, v36
	v_lshl_add_u64 v[18:19], v[4:5], 0, v[0:1]
	global_load_dwordx4 v[50:53], v[2:3], off offset:2048
	global_load_dwordx4 v[6:9], v[18:19], off offset:16
	global_load_dwordx4 v[14:17], v[18:19], off
	global_load_dwordx4 v[58:61], v[2:3], off offset:2560
	global_load_dwordx4 v[10:13], v[18:19], off offset:1040
	global_load_dwordx4 v[26:29], v[18:19], off offset:1024
	global_load_dwordx4 v[46:49], v[2:3], off offset:3072
	global_load_dwordx4 v[22:25], v[18:19], off offset:2064
	global_load_dwordx4 v[30:33], v[18:19], off offset:2048
	global_load_dwordx4 v[42:45], v[2:3], off offset:3584
	s_nop 0
	global_load_dwordx4 v[2:5], v[18:19], off offset:3088
	s_nop 0
	global_load_dwordx4 v[18:21], v[18:19], off offset:3072
	v_cndmask_b32_e32 v37, v203, v37, vcc
	v_lshlrev_b32_e32 v101, 2, v37
	v_xor_b32_e32 v37, 16, v203
	v_cmp_lt_i32_e32 vcc, v37, v36
	v_lshlrev_b32_e32 v98, 2, v76
	v_mov_b32_e32 v99, v1
	v_cndmask_b32_e32 v36, v203, v37, vcc
	v_lshlrev_b32_e32 v144, 2, v36
	v_mov_b64_e32 v[36:37], s[44:45]
	v_mad_u64_u32 v[36:37], s[2:3], v34, s17, v[36:37]
	v_mad_i32_i24 v37, v35, s17, v37
	s_waitcnt lgkmcnt(0)
	v_lshl_add_u64 v[130:131], v[36:37], 0, s[60:61]
	v_lshl_add_u64 v[62:63], v[130:131], 0, v[0:1]
	global_load_dwordx4 v[34:37], v[74:75], off offset:16
	global_load_dwordx4 v[38:41], v[74:75], off
	global_load_dwordx4 v[54:57], v[62:63], off offset:16
	s_nop 0
	global_load_dwordx4 v[62:65], v[62:63], off
	s_waitcnt vmcnt(0)
	v_lshlrev_b32_e32 v66, 16, v53
	v_and_b32_e32 v67, 0xffff0000, v53
	v_lshlrev_b32_e32 v68, 16, v52
	v_and_b32_e32 v69, 0xffff0000, v52
	v_lshlrev_b32_e32 v52, 16, v51
	v_and_b32_e32 v53, 0xffff0000, v51
	v_pk_mul_f32 v[122:123], v[66:67], v[66:67]
	v_pk_mul_f32 v[126:127], v[52:53], v[52:53]
	v_pk_mul_f32 v[124:125], v[68:69], v[68:69]
	v_lshlrev_b32_e32 v94, 16, v61
	v_and_b32_e32 v95, 0xffff0000, v61
	v_pk_mul_f32 v[132:133], v[94:95], v[94:95]
	v_lshlrev_b32_e32 v96, 16, v60
	v_and_b32_e32 v97, 0xffff0000, v60
	v_lshlrev_b32_e32 v60, 16, v59
	v_and_b32_e32 v61, 0xffff0000, v59
	v_pk_mul_f32 v[134:135], v[96:97], v[96:97]
	v_pk_mul_f32 v[136:137], v[60:61], v[60:61]
	v_lshlrev_b32_e32 v140, 16, v48
	v_and_b32_e32 v141, 0xffff0000, v48
	v_lshlrev_b32_e32 v48, 16, v47
	v_pk_mul_f32 v[156:157], v[140:141], v[140:141]
	v_lshlrev_b32_e32 v168, 16, v44
	v_and_b32_e32 v169, 0xffff0000, v44
	v_pk_mul_f32 v[110:111], v[56:57], v[66:67]
	v_pk_mul_f32 v[108:109], v[64:65], v[52:53]
	v_lshlrev_b32_e32 v52, 16, v50
	v_and_b32_e32 v53, 0xffff0000, v50
	v_lshl_add_u64 v[66:67], v[130:131], 0, v[98:99]
	v_pk_mul_f32 v[106:107], v[54:55], v[68:69]
	v_pk_mul_f32 v[128:129], v[52:53], v[52:53]
	v_pk_mul_f32 v[112:113], v[62:63], v[52:53]
	global_load_dwordx4 v[50:53], v[74:75], off offset:1040
	global_load_dwordx4 v[54:57], v[74:75], off offset:1024
	global_load_dwordx4 v[62:65], v[66:67], off offset:16
	s_nop 0
	global_load_dwordx4 v[66:69], v[66:67], off
	v_add_f32_e32 v93, v128, v129
	v_add_f32_e32 v93, v93, v126
	v_add_f32_e32 v93, v93, v127
	v_add_f32_e32 v93, v93, v124
	v_add_f32_e32 v93, v93, v125
	v_add_f32_e32 v93, v93, v122
	v_add_f32_e32 v93, v93, v123
	s_waitcnt vmcnt(1)
	v_pk_mul_f32 v[118:119], v[64:65], v[94:95]
	v_lshlrev_b32_e32 v94, 2, v78
	v_mov_b32_e32 v95, v1
	v_pk_mul_f32 v[114:115], v[62:63], v[96:97]
	s_waitcnt vmcnt(0)
	v_pk_mul_f32 v[116:117], v[68:69], v[60:61]
	v_lshlrev_b32_e32 v60, 16, v58
	v_and_b32_e32 v61, 0xffff0000, v58
	v_lshl_add_u64 v[96:97], v[130:131], 0, v[94:95]
	v_pk_mul_f32 v[138:139], v[60:61], v[60:61]
	v_pk_mul_f32 v[120:121], v[66:67], v[60:61]
	global_load_dwordx4 v[58:61], v[74:75], off offset:2064
	global_load_dwordx4 v[62:65], v[74:75], off offset:2048
	global_load_dwordx4 v[66:69], v[96:97], off offset:16
	global_load_dwordx4 v[146:149], v[96:97], off
	v_lshlrev_b32_e32 v96, 16, v49
	v_and_b32_e32 v97, 0xffff0000, v49
	v_pk_mul_f32 v[154:155], v[96:97], v[96:97]
	v_and_b32_e32 v49, 0xffff0000, v47
	v_pk_mul_f32 v[158:159], v[48:49], v[48:49]
	v_add_f32_e32 v93, v93, v138
	v_add_f32_e32 v93, v93, v139
	v_add_f32_e32 v93, v93, v136
	v_add_f32_e32 v93, v93, v137
	v_add_f32_e32 v93, v93, v134
	v_add_f32_e32 v93, v93, v135
	v_add_f32_e32 v93, v93, v132
	v_add_f32_e32 v93, v93, v133
	s_waitcnt vmcnt(1)
	v_pk_mul_f32 v[164:165], v[68:69], v[96:97]
	v_lshlrev_b32_e32 v96, 2, v80
	v_mov_b32_e32 v97, v1
	s_waitcnt vmcnt(0)
	v_pk_mul_f32 v[142:143], v[148:149], v[48:49]
	v_lshlrev_b32_e32 v48, 16, v46
	v_and_b32_e32 v49, 0xffff0000, v46
	v_lshl_add_u64 v[130:131], v[130:131], 0, v[96:97]
	v_pk_mul_f32 v[140:141], v[66:67], v[140:141]
	v_pk_mul_f32 v[160:161], v[48:49], v[48:49]
	v_pk_mul_f32 v[162:163], v[146:147], v[48:49]
	global_load_dwordx4 v[46:49], v[74:75], off offset:3088
	global_load_dwordx4 v[66:69], v[74:75], off offset:3072
	global_load_dwordx4 v[146:149], v[130:131], off offset:16
	global_load_dwordx4 v[150:153], v[130:131], off
	v_add_f32_e32 v93, v93, v160
	v_add_f32_e32 v93, v93, v161
	v_add_f32_e32 v93, v93, v158
	v_add_f32_e32 v93, v93, v159
	v_add_f32_e32 v93, v93, v156
	v_lshlrev_b32_e32 v130, 16, v45
	v_and_b32_e32 v131, 0xffff0000, v45
	v_pk_mul_f32 v[44:45], v[168:169], v[168:169]
	v_add_f32_e32 v93, v93, v157
	v_add_f32_e32 v93, v93, v154
	v_add_f32_e32 v93, v93, v155
	v_pk_mul_f32 v[166:167], v[130:131], v[130:131]
	s_waitcnt vmcnt(1)
; __global__ void __launch_bounds__(512, 2) fwd_kernel(Params p) {
;     ...
;             for (int j = 0; j < 32; ++j) s += ov[j] * ov[j];
; #pragma unroll
;             for (int o = 1; o < 32; o <<= 1) s += __shfl_xor(s, o);
;             const float rs = __builtin_amdgcn_rsqf(s * (1.f / D) + EPS);
;             float s2 = 0.f;
; #pragma unroll
;             for (int j = 0; j < 4; ++j)
; #pragma unroll
;                 for (int q = 0; q < 2; ++q) { const int c = 8 * l32 + 256 * j + 4 * q;
;                     const f32x4 pg = *(const f32x4*)(p.post_norm + l * D + c), gt = *(const f32x4*)(mrow + 2 * D + c);
; #pragma unroll
;                     for (int e = 0; e < 4; ++e) { const float v = xv[2 * j + q][e] + gt[e] * ov[8 * j + 4 * q + e] * rs * pg[e]; ov[8 * j + 4 * q + e] = v; s2 += v * v; } }
;             if (!isctx && !dry) { float* orw = p.out + ((size_t)b * SEQ + tok - CTXL) * D;
; #pragma unroll
;                 for (int j = 0; j < 4; ++j)
; #pragma unroll
;                     for (int q = 0; q < 2; ++q) *(f32x4*)(orw + 8 * l32 + 256 * j + 4 * q) = (f32x4){ov[8 * j + 4 * q], ov[8 * j + 4 * q + 1], ov[8 * j + 4 * q + 2], ov[8 * j + 4 * q + 3]}; }
;             if (l == 0) {
; #pragma unroll
;                 for (int o = 1; o < 32; o <<= 1) s2 += __shfl_xor(s2, o);
	v_pk_mul_f32 v[146:147], v[146:147], v[168:169]
	v_lshlrev_b32_e32 v168, 16, v43
	v_and_b32_e32 v169, 0xffff0000, v43
	v_pk_mul_f32 v[170:171], v[168:169], v[168:169]
	s_waitcnt vmcnt(0)
	v_pk_mul_f32 v[152:153], v[152:153], v[168:169]
	v_lshlrev_b32_e32 v168, 16, v42
	v_and_b32_e32 v169, 0xffff0000, v42
	v_pk_mul_f32 v[42:43], v[168:169], v[168:169]
	v_pk_mul_f32 v[150:151], v[150:151], v[168:169]
	v_add_f32_e32 v42, v93, v42
	v_add_f32_e32 v42, v42, v43
	v_add_f32_e32 v42, v42, v170
	v_add_f32_e32 v42, v42, v171
	v_add_f32_e32 v42, v42, v44
	v_add_f32_e32 v42, v42, v45
	v_add_f32_e32 v42, v42, v166
	v_add_f32_e32 v42, v42, v167
	s_waitcnt lgkmcnt(0)
	s_nop 1
	v_add_f32_dpp v42, v42, v42 quad_perm:[1,0,3,2] row_mask:0xf bank_mask:0xf
	s_waitcnt lgkmcnt(0)
	s_nop 1
	v_add_f32_dpp v42, v42, v42 quad_perm:[2,3,0,1] row_mask:0xf bank_mask:0xf
	s_waitcnt lgkmcnt(0)
	s_nop 1
	v_add_f32_dpp v42, v42, v42 row_half_mirror row_mask:0xf bank_mask:0xf
	s_waitcnt lgkmcnt(0)
	s_nop 1
	v_add_f32_dpp v42, v42, v42 row_mirror row_mask:0xf bank_mask:0xf
	s_waitcnt lgkmcnt(0)
	v_mov_b32_e32 v43, v42
	s_nop 1
	v_permlane16_swap_b32_e32 v43, v42
	v_add_f32_e32 v42, v42, v43
	v_fmamk_f32 v42, v42, 0x3a800000, v202
	v_rsq_f32_e32 v122, v42
	s_nop 0
	v_pk_mul_f32 v[42:43], v[122:123], v[112:113] op_sel_hi:[0,1]
	v_pk_fma_f32 v[42:43], v[38:39], v[42:43], v[14:15]
	v_pk_mul_f32 v[14:15], v[122:123], v[108:109] op_sel_hi:[0,1]
	v_pk_fma_f32 v[44:45], v[40:41], v[14:15], v[16:17]
	v_pk_mul_f32 v[14:15], v[122:123], v[106:107] op_sel_hi:[0,1]
	v_pk_fma_f32 v[38:39], v[34:35], v[14:15], v[6:7]
	v_pk_mul_f32 v[6:7], v[122:123], v[110:111] op_sel_hi:[0,1]
	v_pk_fma_f32 v[40:41], v[36:37], v[6:7], v[8:9]
	v_pk_mul_f32 v[6:7], v[122:123], v[120:121] op_sel_hi:[0,1]
	v_pk_fma_f32 v[34:35], v[54:55], v[6:7], v[26:27]
	v_pk_mul_f32 v[6:7], v[122:123], v[116:117] op_sel_hi:[0,1]
	v_pk_fma_f32 v[36:37], v[56:57], v[6:7], v[28:29]
	v_pk_mul_f32 v[6:7], v[122:123], v[114:115] op_sel_hi:[0,1]
	v_pk_fma_f32 v[26:27], v[50:51], v[6:7], v[10:11]
	v_pk_mul_f32 v[6:7], v[122:123], v[118:119] op_sel_hi:[0,1]
	v_pk_fma_f32 v[28:29], v[52:53], v[6:7], v[12:13]
	v_pk_mul_f32 v[6:7], v[122:123], v[162:163] op_sel_hi:[0,1]
	v_pk_fma_f32 v[14:15], v[62:63], v[6:7], v[30:31]
	v_pk_mul_f32 v[6:7], v[122:123], v[142:143] op_sel_hi:[0,1]
	v_pk_fma_f32 v[16:17], v[64:65], v[6:7], v[32:33]
	v_pk_mul_f32 v[6:7], v[122:123], v[140:141] op_sel_hi:[0,1]
	v_pk_fma_f32 v[10:11], v[58:59], v[6:7], v[22:23]
	v_pk_mul_f32 v[6:7], v[122:123], v[164:165] op_sel_hi:[0,1]
	v_pk_fma_f32 v[12:13], v[60:61], v[6:7], v[24:25]
	v_pk_mul_f32 v[6:7], v[122:123], v[150:151] op_sel_hi:[0,1]
	v_pk_fma_f32 v[6:7], v[66:67], v[6:7], v[18:19]
	v_pk_mul_f32 v[18:19], v[122:123], v[146:147] op_sel_hi:[0,1]
	v_pk_fma_f32 v[2:3], v[46:47], v[18:19], v[2:3]
	v_pk_mul_f32 v[18:19], v[148:149], v[130:131]
	v_pk_mul_f32 v[8:9], v[122:123], v[152:153] op_sel_hi:[0,1]
	v_pk_mul_f32 v[18:19], v[122:123], v[18:19] op_sel_hi:[0,1]
	v_pk_fma_f32 v[8:9], v[68:69], v[8:9], v[20:21]
	v_pk_fma_f32 v[4:5], v[48:49], v[18:19], v[4:5]
	s_and_saveexec_b64 s[2:3], s[38:39]
	s_cbranch_execz .LBB0_1283
	v_mov_b32_e32 v103, v1
	v_lshlrev_b64 v[18:19], 12, v[102:103]
	v_lshl_add_u64 v[18:19], v[104:105], 0, v[18:19]
	s_mov_b32 s24, 0xfff00000
	v_lshl_add_u64 v[18:19], v[18:19], 0, v[0:1]
	s_mov_b32 s25, -1
	v_lshl_add_u64 v[20:21], v[18:19], 0, s[24:25]
	v_add_co_u32_e32 v18, vcc, 0xfff00000, v18
	s_nop 1
	v_addc_co_u32_e32 v19, vcc, -1, v19, vcc
	global_store_dwordx4 v[18:19], v[42:45], off
	global_store_dwordx4 v[20:21], v[38:41], off offset:16
	global_store_dwordx4 v[20:21], v[34:37], off offset:1024
	global_store_dwordx4 v[20:21], v[26:29], off offset:1040
	global_store_dwordx4 v[20:21], v[14:17], off offset:2048
	global_store_dwordx4 v[20:21], v[10:13], off offset:2064
	global_store_dwordx4 v[20:21], v[6:9], off offset:3072
	global_store_dwordx4 v[20:21], v[2:5], off offset:3088
.LBB0_1283:
	s_or_b64 exec, exec, s[2:3]
	s_andn2_b64 vcc, exec, s[76:77]
	s_cbranch_vccnz .LBB0_1271
	v_pk_mul_f32 v[18:19], v[42:43], v[42:43]
	v_pk_mul_f32 v[20:21], v[44:45], v[44:45]
	v_add_f32_e32 v18, v18, v19
	v_add_f32_e32 v18, v18, v20
	v_pk_mul_f32 v[22:23], v[38:39], v[38:39]
	v_add_f32_e32 v18, v18, v21
	v_add_f32_e32 v18, v18, v22
	v_pk_mul_f32 v[24:25], v[40:41], v[40:41]
	v_add_f32_e32 v18, v18, v23
	v_add_f32_e32 v18, v18, v24
	v_pk_mul_f32 v[30:31], v[34:35], v[34:35]
	v_add_f32_e32 v18, v18, v25
	v_add_f32_e32 v18, v18, v30
	v_pk_mul_f32 v[32:33], v[36:37], v[36:37]
	v_add_f32_e32 v18, v18, v31
	v_add_f32_e32 v18, v18, v32
	v_pk_mul_f32 v[46:47], v[26:27], v[26:27]
	v_add_f32_e32 v18, v18, v33
	v_add_f32_e32 v18, v18, v46
	v_pk_mul_f32 v[48:49], v[28:29], v[28:29]
	v_add_f32_e32 v18, v18, v47
	v_add_f32_e32 v18, v18, v48
	v_pk_mul_f32 v[50:51], v[14:15], v[14:15]
	v_add_f32_e32 v18, v18, v49
	v_add_f32_e32 v18, v18, v50
	v_pk_mul_f32 v[52:53], v[16:17], v[16:17]
	v_add_f32_e32 v18, v18, v51
	v_add_f32_e32 v18, v18, v52
	v_pk_mul_f32 v[54:55], v[10:11], v[10:11]
	v_add_f32_e32 v18, v18, v53
	v_add_f32_e32 v18, v18, v54
	v_pk_mul_f32 v[56:57], v[12:13], v[12:13]
	v_add_f32_e32 v18, v18, v55
	v_add_f32_e32 v18, v18, v56
	v_pk_mul_f32 v[58:59], v[6:7], v[6:7]
	v_add_f32_e32 v18, v18, v57
	v_add_f32_e32 v18, v18, v58
	v_pk_mul_f32 v[60:61], v[8:9], v[8:9]
	v_add_f32_e32 v18, v18, v59
	v_add_f32_e32 v18, v18, v60
	v_pk_mul_f32 v[62:63], v[2:3], v[2:3]
	v_add_f32_e32 v18, v18, v61
	v_add_f32_e32 v18, v18, v62
	v_pk_mul_f32 v[64:65], v[4:5], v[4:5]
	v_add_f32_e32 v18, v18, v63
	v_add_f32_e32 v18, v18, v64
	v_add_f32_e32 v18, v18, v65
	s_mov_b64 s[2:3], 0x63000
	v_ashrrev_i32_e32 v93, 31, v92
	v_mov_b32_e32 v99, v1
	v_mov_b32_e32 v95, v1
	s_waitcnt lgkmcnt(0)
; __device__ __forceinline__ unsigned cvtpk(float lo, float hi) { f32x2 v = {lo, hi}; bf16x2_t b = __builtin_convertvector(v, bf16x2_t); return __builtin_bit_cast(unsigned, b); }
; __global__ void __launch_bounds__(512, 2) fwd_kernel(Params p) {
;     ...
;                 for (int o = 1; o < 32; o <<= 1) s2 += __shfl_xor(s2, o);
;                 if (!dry) {
;                 const float rs2 = __builtin_amdgcn_rsqf(s2 * (1.f / D) + EPS);
;                 const float* m1 = modb + ((size_t)33 + (isctx ? 32 : b)) * 3072;
; #pragma unroll
;                 for (int j = 0; j < 4; ++j) { float hv[8];
; #pragma unroll
;                     for (int q = 0; q < 2; ++q) { const int c = 8 * l32 + 256 * j + 4 * q;
;                         const f32x4 g = *(const f32x4*)(p.pre_norm + D + c), sh = *(const f32x4*)(m1 + c), scl = *(const f32x4*)(m1 + D + c);
; #pragma unroll
;                         for (int e = 0; e < 4; ++e) hv[4 * q + e] = ov[8 * j + 4 * q + e] * rs2 * g[e] * (1.f + scl[e]) + sh[e]; }
;                     u32x4 hw; hw.x = cvtpk(hv[0], hv[1]); hw.y = cvtpk(hv[2], hv[3]); hw.z = cvtpk(hv[4], hv[5]); hw.w = cvtpk(hv[6], hv[7]);
;                     *(u32x4*)(H + (size_t)r * D + 8 * l32 + 256 * j) = hw; }
;                 if (l32 == 0) { ssq_q[r] = 0.f; ssq_kv[r] = 0.f; }
	s_nop 1
	v_add_f32_dpp v18, v18, v18 quad_perm:[1,0,3,2] row_mask:0xf bank_mask:0xf
	v_mov_b32_e32 v97, v1
	s_waitcnt lgkmcnt(0)
	s_nop 1
	v_add_f32_dpp v18, v18, v18 quad_perm:[2,3,0,1] row_mask:0xf bank_mask:0xf
	s_waitcnt lgkmcnt(0)
	s_nop 1
	v_add_f32_dpp v18, v18, v18 row_half_mirror row_mask:0xf bank_mask:0xf
	s_waitcnt lgkmcnt(0)
	s_nop 1
	v_add_f32_dpp v18, v18, v18 row_mirror row_mask:0xf bank_mask:0xf
	s_waitcnt lgkmcnt(0)
	v_mov_b32_e32 v19, v18
	s_nop 1
	v_permlane16_swap_b32_e32 v19, v18
	v_add_f32_e32 v18, v18, v19
	v_fmamk_f32 v18, v18, 0x3a800000, v202
	v_rsq_f32_e32 v54, v18
	v_mul_hi_i32_i24_e32 v19, 0x3000, v100
	v_mul_i32_i24_e32 v18, 0x3000, v100
	v_lshl_add_u64 v[18:19], s[44:45], 0, v[18:19]
	v_lshl_add_u64 v[60:61], v[18:19], 0, s[2:3]
	s_mov_b64 s[2:3], 0x64000
	v_lshl_add_u64 v[58:59], v[18:19], 0, s[2:3]
	v_lshlrev_b64 v[18:19], 11, v[92:93]
	v_lshl_add_u64 v[30:31], v[60:61], 0, v[0:1]
	v_lshl_add_u64 v[62:63], v[58:59], 0, v[0:1]
	v_lshl_add_u64 v[56:57], v[72:73], 0, v[18:19]
	global_load_dwordx4 v[18:21], v[82:83], off offset:16
	global_load_dwordx4 v[50:53], v[82:83], off
	global_load_dwordx4 v[22:25], v[30:31], off offset:16
	global_load_dwordx4 v[46:49], v[30:31], off
	s_nop 0
	global_load_dwordx4 v[30:33], v[62:63], off offset:16
	s_nop 0
	global_load_dwordx4 v[62:65], v[62:63], off
	v_pk_mul_f32 v[38:39], v[54:55], v[38:39] op_sel_hi:[0,1]
	v_pk_mul_f32 v[42:43], v[54:55], v[42:43] op_sel_hi:[0,1]
	v_pk_mul_f32 v[44:45], v[54:55], v[44:45] op_sel_hi:[0,1]
	v_pk_mul_f32 v[34:35], v[54:55], v[34:35] op_sel_hi:[0,1]
	v_pk_mul_f32 v[26:27], v[54:55], v[26:27] op_sel_hi:[0,1]
	v_pk_mul_f32 v[10:11], v[54:55], v[10:11] op_sel_hi:[0,1]
	v_pk_mul_f32 v[14:15], v[54:55], v[14:15] op_sel_hi:[0,1]
	v_pk_mul_f32 v[16:17], v[54:55], v[16:17] op_sel_hi:[0,1]
	v_pk_mul_f32 v[2:3], v[54:55], v[2:3] op_sel_hi:[0,1]
	v_pk_mul_f32 v[6:7], v[54:55], v[6:7] op_sel_hi:[0,1]
	v_pk_mul_f32 v[8:9], v[54:55], v[8:9] op_sel_hi:[0,1]
	s_waitcnt vmcnt(5)
	v_pk_mul_f32 v[18:19], v[18:19], v[38:39]
	s_waitcnt vmcnt(4)
	v_pk_mul_f32 v[42:43], v[50:51], v[42:43]
	s_waitcnt vmcnt(1)
	v_pk_add_f32 v[30:31], v[30:31], 1.0 op_sel_hi:[1,0]
	s_waitcnt vmcnt(0)
	v_pk_add_f32 v[50:51], v[62:63], 1.0 op_sel_hi:[1,0]
	v_pk_fma_f32 v[22:23], v[30:31], v[18:19], v[22:23]
	v_pk_mul_f32 v[18:19], v[54:55], v[40:41] op_sel_hi:[0,1]
	v_pk_fma_f32 v[42:43], v[50:51], v[42:43], v[46:47]
	v_pk_mul_f32 v[44:45], v[52:53], v[44:45]
	v_pk_add_f32 v[46:47], v[64:65], 1.0 op_sel_hi:[1,0]
	v_pk_mul_f32 v[18:19], v[20:21], v[18:19]
	v_pk_add_f32 v[20:21], v[32:33], 1.0 op_sel_hi:[1,0]
	v_pk_fma_f32 v[44:45], v[46:47], v[44:45], v[48:49]
	v_pk_fma_f32 v[24:25], v[20:21], v[18:19], v[24:25]
	v_cvt_pk_bf16_f32 v18, v42, v43
	v_cvt_pk_bf16_f32 v19, v44, v45
	v_cvt_pk_bf16_f32 v20, v22, v23
	v_cvt_pk_bf16_f32 v21, v24, v25
	global_store_dwordx4 v[56:57], v[18:21], off
	v_lshl_add_u64 v[38:39], v[60:61], 0, v[98:99]
	v_lshl_add_u64 v[46:47], v[58:59], 0, v[98:99]
	global_load_dwordx4 v[18:21], v[84:85], off offset:16
	global_load_dwordx4 v[22:25], v[84:85], off
	global_load_dwordx4 v[30:33], v[38:39], off offset:16
	s_nop 0
	global_load_dwordx4 v[38:41], v[38:39], off
	s_nop 0
	global_load_dwordx4 v[42:45], v[46:47], off offset:16
	s_nop 0
	global_load_dwordx4 v[46:49], v[46:47], off
	s_waitcnt vmcnt(5)
	v_pk_mul_f32 v[18:19], v[18:19], v[26:27]
	s_waitcnt vmcnt(4)
	v_pk_mul_f32 v[22:23], v[22:23], v[34:35]
	s_waitcnt vmcnt(1)
	v_pk_add_f32 v[26:27], v[42:43], 1.0 op_sel_hi:[1,0]
	s_waitcnt vmcnt(0)
	v_pk_add_f32 v[34:35], v[46:47], 1.0 op_sel_hi:[1,0]
	v_pk_fma_f32 v[26:27], v[26:27], v[18:19], v[30:31]
	v_pk_fma_f32 v[22:23], v[34:35], v[22:23], v[38:39]
	v_pk_mul_f32 v[34:35], v[54:55], v[36:37] op_sel_hi:[0,1]
	v_pk_mul_f32 v[18:19], v[54:55], v[28:29] op_sel_hi:[0,1]
	v_pk_mul_f32 v[24:25], v[24:25], v[34:35]
	v_pk_add_f32 v[34:35], v[48:49], 1.0 op_sel_hi:[1,0]
	v_pk_mul_f32 v[18:19], v[20:21], v[18:19]
	v_pk_add_f32 v[20:21], v[44:45], 1.0 op_sel_hi:[1,0]
	v_pk_fma_f32 v[24:25], v[34:35], v[24:25], v[40:41]
	v_pk_fma_f32 v[28:29], v[20:21], v[18:19], v[32:33]
	v_cvt_pk_bf16_f32 v18, v22, v23
	v_cvt_pk_bf16_f32 v19, v24, v25
	v_cvt_pk_bf16_f32 v20, v26, v27
	v_cvt_pk_bf16_f32 v21, v28, v29
	global_store_dwordx4 v[56:57], v[18:21], off offset:512
	v_lshl_add_u64 v[30:31], v[60:61], 0, v[94:95]
	v_lshl_add_u64 v[38:39], v[58:59], 0, v[94:95]
	global_load_dwordx4 v[18:21], v[86:87], off offset:16
	global_load_dwordx4 v[22:25], v[86:87], off
	global_load_dwordx4 v[26:29], v[30:31], off offset:16
	s_nop 0
	global_load_dwordx4 v[30:33], v[30:31], off
	s_nop 0
	global_load_dwordx4 v[34:37], v[38:39], off offset:16
	s_nop 0
	global_load_dwordx4 v[38:41], v[38:39], off
	s_waitcnt vmcnt(5)
	v_pk_mul_f32 v[10:11], v[18:19], v[10:11]
	s_waitcnt vmcnt(4)
	v_pk_mul_f32 v[14:15], v[22:23], v[14:15]
	s_waitcnt vmcnt(1)
	v_pk_add_f32 v[18:19], v[34:35], 1.0 op_sel_hi:[1,0]
	s_waitcnt vmcnt(0)
	v_pk_add_f32 v[22:23], v[38:39], 1.0 op_sel_hi:[1,0]
	v_pk_fma_f32 v[18:19], v[18:19], v[10:11], v[26:27]
	v_pk_mul_f32 v[10:11], v[54:55], v[12:13] op_sel_hi:[0,1]
	v_pk_fma_f32 v[14:15], v[22:23], v[14:15], v[30:31]
	v_pk_mul_f32 v[16:17], v[24:25], v[16:17]
	v_pk_add_f32 v[22:23], v[40:41], 1.0 op_sel_hi:[1,0]
	v_pk_mul_f32 v[10:11], v[20:21], v[10:11]
	v_pk_add_f32 v[12:13], v[36:37], 1.0 op_sel_hi:[1,0]
	v_pk_fma_f32 v[16:17], v[22:23], v[16:17], v[32:33]
	v_pk_fma_f32 v[20:21], v[12:13], v[10:11], v[28:29]
	v_cvt_pk_bf16_f32 v10, v14, v15
	v_cvt_pk_bf16_f32 v11, v16, v17
	v_cvt_pk_bf16_f32 v12, v18, v19
	v_cvt_pk_bf16_f32 v13, v20, v21
	global_store_dwordx4 v[56:57], v[10:13], off offset:1024
	v_lshl_add_u64 v[22:23], v[60:61], 0, v[96:97]
	v_lshl_add_u64 v[30:31], v[58:59], 0, v[96:97]
	global_load_dwordx4 v[10:13], v[88:89], off offset:16
	global_load_dwordx4 v[14:17], v[88:89], off
	global_load_dwordx4 v[18:21], v[22:23], off offset:16
	s_nop 0
	global_load_dwordx4 v[22:25], v[22:23], off
	s_nop 0
	global_load_dwordx4 v[26:29], v[30:31], off offset:16
	s_nop 0
	global_load_dwordx4 v[30:33], v[30:31], off
	s_waitcnt vmcnt(5)
	v_pk_mul_f32 v[2:3], v[10:11], v[2:3]
	s_waitcnt vmcnt(4)
	v_pk_mul_f32 v[6:7], v[14:15], v[6:7]
	s_waitcnt vmcnt(1)
	v_pk_add_f32 v[10:11], v[26:27], 1.0 op_sel_hi:[1,0]
	s_waitcnt vmcnt(0)
	v_pk_add_f32 v[14:15], v[30:31], 1.0 op_sel_hi:[1,0]
	v_pk_fma_f32 v[10:11], v[10:11], v[2:3], v[18:19]
	v_pk_mul_f32 v[2:3], v[54:55], v[4:5] op_sel_hi:[0,1]
	v_pk_fma_f32 v[6:7], v[14:15], v[6:7], v[22:23]
	v_pk_mul_f32 v[8:9], v[16:17], v[8:9]
	v_pk_add_f32 v[14:15], v[32:33], 1.0 op_sel_hi:[1,0]
	v_pk_mul_f32 v[2:3], v[12:13], v[2:3]
	v_pk_add_f32 v[4:5], v[28:29], 1.0 op_sel_hi:[1,0]
	v_pk_fma_f32 v[8:9], v[14:15], v[8:9], v[24:25]
	v_pk_fma_f32 v[12:13], v[4:5], v[2:3], v[20:21]
	v_cvt_pk_bf16_f32 v2, v6, v7
	v_cvt_pk_bf16_f32 v3, v8, v9
	v_cvt_pk_bf16_f32 v4, v10, v11
	v_cvt_pk_bf16_f32 v5, v12, v13
	global_store_dwordx4 v[56:57], v[2:5], off offset:1536
	s_and_saveexec_b64 s[2:3], s[0:1]
	s_cbranch_execz .LBB0_1270
; __global__ void __launch_bounds__(512, 2) fwd_kernel(Params p) {
;     ...
;                 if (l32 == 0) { ssq_q[r] = 0.f; ssq_kv[r] = 0.f; }
	v_readlane_b32 s24, v252, 9
	v_lshlrev_b64 v[2:3], 2, v[92:93]
	v_readlane_b32 s25, v252, 10
	s_nop 1
	v_lshl_add_u64 v[4:5], s[24:25], 0, v[2:3]
	v_readlane_b32 s24, v252, 13
	v_readlane_b32 s25, v252, 14
	s_nop 1
	v_lshl_add_u64 v[2:3], s[24:25], 0, v[2:3]
	global_store_dword v[2:3], v1, off
	global_store_dword v[4:5], v1, off
	s_branch .LBB0_1270
